# diff loop: restored the full MFMA-result wait (s_nop 7) before the first max3 read on the far-tile path (hazard-table compliance after the earlier max-chain trim)
# baseline (speedup 1.0000x reference)
.LBB0_481:
	s_or_b64 exec, exec, s[0:1]
	s_nop 7
	v_max3_f32 v170, v82, v66, v83
	v_max3_f32 v170, v170, v67, v84
	v_max3_f32 v170, v170, v68, v85
	v_max3_f32 v170, v170, v69, v86
	v_cndmask_b32_e32 v0, 0, v149, vcc
	v_max3_f32 v170, v170, v70, v87
	s_mov_b32 s0, 0x41200000
	v_max3_f32 v170, v170, v71, v88
	s_nop 0
	v_max3_f32 v170, v170, v72, v89
	s_nop 0
	v_max3_f32 v170, v170, v73, v90
	s_nop 0
	v_max3_f32 v170, v170, v74, v91
	s_nop 0
	v_max3_f32 v170, v170, v75, v92
	s_nop 0
	v_max3_f32 v170, v170, v76, v93
	s_nop 0
	v_max3_f32 v170, v170, v77, v94
	s_nop 0
	v_max3_f32 v170, v170, v78, v95
	s_nop 0
	v_max3_f32 v170, v170, v79, v96
	s_nop 0
	v_max3_f32 v170, v170, v80, v97
	s_nop 0
	v_max_f32_e32 v170, v170, v81
	v_mov_b32_e32 v171, v170
	s_nop 1
	v_permlane32_swap_b32_e32 v171, v170
	v_max_f32_e32 v170, v170, v171
	v_add_f32_e32 v170, v0, v170
	v_sub_f32_e32 v171, v170, v150
	v_cmp_lt_f32_e32 vcc, s0, v171
	s_cbranch_vccnz .Ldf_rescale
